# tr_item for W_dkv: all 32 row loads and gain loads batched before one wait (was 32 serialized round trips)
# speedup vs baseline: 1.0082x; 1.0024x over previous
.LBB0_120:
	v_add_u32_e32 v164, 0, v14
	v_mad_i64_i32 v[166:167], s[20:21], v164, s16, v[12:13]
	global_load_dword v100, v[166:167], off nt
	v_add_u32_e32 v164, 2, v14
	v_mad_i64_i32 v[166:167], s[20:21], v164, s16, v[12:13]
	global_load_dword v101, v[166:167], off nt
	v_add_u32_e32 v164, 4, v14
	v_mad_i64_i32 v[166:167], s[20:21], v164, s16, v[12:13]
	global_load_dword v102, v[166:167], off nt
	v_add_u32_e32 v164, 6, v14
	v_mad_i64_i32 v[166:167], s[20:21], v164, s16, v[12:13]
	global_load_dword v103, v[166:167], off nt
	v_add_u32_e32 v164, 8, v14
	v_mad_i64_i32 v[166:167], s[20:21], v164, s16, v[12:13]
	global_load_dword v104, v[166:167], off nt
	v_add_u32_e32 v164, 10, v14
	v_mad_i64_i32 v[166:167], s[20:21], v164, s16, v[12:13]
	global_load_dword v105, v[166:167], off nt
	v_add_u32_e32 v164, 12, v14
	v_mad_i64_i32 v[166:167], s[20:21], v164, s16, v[12:13]
	global_load_dword v106, v[166:167], off nt
	v_add_u32_e32 v164, 14, v14
	v_mad_i64_i32 v[166:167], s[20:21], v164, s16, v[12:13]
	global_load_dword v107, v[166:167], off nt
	v_add_u32_e32 v164, 16, v14
	v_mad_i64_i32 v[166:167], s[20:21], v164, s16, v[12:13]
	global_load_dword v108, v[166:167], off nt
	v_add_u32_e32 v164, 18, v14
	v_mad_i64_i32 v[166:167], s[20:21], v164, s16, v[12:13]
	global_load_dword v109, v[166:167], off nt
	v_add_u32_e32 v164, 20, v14
	v_mad_i64_i32 v[166:167], s[20:21], v164, s16, v[12:13]
	global_load_dword v110, v[166:167], off nt
	v_add_u32_e32 v164, 22, v14
	v_mad_i64_i32 v[166:167], s[20:21], v164, s16, v[12:13]
	global_load_dword v111, v[166:167], off nt
	v_add_u32_e32 v164, 24, v14
	v_mad_i64_i32 v[166:167], s[20:21], v164, s16, v[12:13]
	global_load_dword v112, v[166:167], off nt
	v_add_u32_e32 v164, 26, v14
	v_mad_i64_i32 v[166:167], s[20:21], v164, s16, v[12:13]
	global_load_dword v113, v[166:167], off nt
	v_add_u32_e32 v164, 28, v14
	v_mad_i64_i32 v[166:167], s[20:21], v164, s16, v[12:13]
	global_load_dword v114, v[166:167], off nt
	v_add_u32_e32 v164, 30, v14
	v_mad_i64_i32 v[166:167], s[20:21], v164, s16, v[12:13]
	global_load_dword v115, v[166:167], off nt
	v_add_u32_e32 v164, 32, v14
	v_mad_i64_i32 v[166:167], s[20:21], v164, s16, v[12:13]
	global_load_dword v116, v[166:167], off nt
	v_add_u32_e32 v164, 34, v14
	v_mad_i64_i32 v[166:167], s[20:21], v164, s16, v[12:13]
	global_load_dword v117, v[166:167], off nt
	v_add_u32_e32 v164, 36, v14
	v_mad_i64_i32 v[166:167], s[20:21], v164, s16, v[12:13]
	global_load_dword v118, v[166:167], off nt
	v_add_u32_e32 v164, 38, v14
	v_mad_i64_i32 v[166:167], s[20:21], v164, s16, v[12:13]
	global_load_dword v119, v[166:167], off nt
	v_add_u32_e32 v164, 40, v14
	v_mad_i64_i32 v[166:167], s[20:21], v164, s16, v[12:13]
	global_load_dword v120, v[166:167], off nt
	v_add_u32_e32 v164, 42, v14
	v_mad_i64_i32 v[166:167], s[20:21], v164, s16, v[12:13]
	global_load_dword v121, v[166:167], off nt
	v_add_u32_e32 v164, 44, v14
	v_mad_i64_i32 v[166:167], s[20:21], v164, s16, v[12:13]
	global_load_dword v122, v[166:167], off nt
	v_add_u32_e32 v164, 46, v14
	v_mad_i64_i32 v[166:167], s[20:21], v164, s16, v[12:13]
	global_load_dword v123, v[166:167], off nt
	v_add_u32_e32 v164, 48, v14
	v_mad_i64_i32 v[166:167], s[20:21], v164, s16, v[12:13]
	global_load_dword v124, v[166:167], off nt
	v_add_u32_e32 v164, 50, v14
	v_mad_i64_i32 v[166:167], s[20:21], v164, s16, v[12:13]
	global_load_dword v125, v[166:167], off nt
	v_add_u32_e32 v164, 52, v14
	v_mad_i64_i32 v[166:167], s[20:21], v164, s16, v[12:13]
	global_load_dword v126, v[166:167], off nt
	v_add_u32_e32 v164, 54, v14
	v_mad_i64_i32 v[166:167], s[20:21], v164, s16, v[12:13]
	global_load_dword v127, v[166:167], off nt
	v_add_u32_e32 v164, 56, v14
	v_mad_i64_i32 v[166:167], s[20:21], v164, s16, v[12:13]
	global_load_dword v128, v[166:167], off nt
	v_add_u32_e32 v164, 58, v14
	v_mad_i64_i32 v[166:167], s[20:21], v164, s16, v[12:13]
	global_load_dword v129, v[166:167], off nt
	v_add_u32_e32 v164, 60, v14
	v_mad_i64_i32 v[166:167], s[20:21], v164, s16, v[12:13]
	global_load_dword v130, v[166:167], off nt
	v_add_u32_e32 v164, 62, v14
	v_mad_i64_i32 v[166:167], s[20:21], v164, s16, v[12:13]
	global_load_dword v131, v[166:167], off nt
	s_and_b64 vcc, exec, s[4:5]
	s_cbranch_vccnz .Ltrm_nogain
	global_load_dword v132, v[16:17], off offset:-120 nt
	global_load_dword v133, v[16:17], off offset:-112 nt
	global_load_dword v134, v[16:17], off offset:-104 nt
	global_load_dword v135, v[16:17], off offset:-96 nt
	global_load_dword v136, v[16:17], off offset:-88 nt
	global_load_dword v137, v[16:17], off offset:-80 nt
	global_load_dword v138, v[16:17], off offset:-72 nt
	global_load_dword v139, v[16:17], off offset:-64 nt
	global_load_dword v140, v[16:17], off offset:-56 nt
	global_load_dword v141, v[16:17], off offset:-48 nt
	global_load_dword v142, v[16:17], off offset:-40 nt
	global_load_dword v143, v[16:17], off offset:-32 nt
	global_load_dword v144, v[16:17], off offset:-24 nt
	global_load_dword v145, v[16:17], off offset:-16 nt
	global_load_dword v146, v[16:17], off offset:-8 nt
	global_load_dword v147, v[16:17], off offset:0 nt
	global_load_dword v148, v[16:17], off offset:8 nt
	global_load_dword v149, v[16:17], off offset:16 nt
	global_load_dword v150, v[16:17], off offset:24 nt
	global_load_dword v151, v[16:17], off offset:32 nt
	global_load_dword v152, v[16:17], off offset:40 nt
	global_load_dword v153, v[16:17], off offset:48 nt
	global_load_dword v154, v[16:17], off offset:56 nt
	global_load_dword v155, v[16:17], off offset:64 nt
	global_load_dword v156, v[16:17], off offset:72 nt
	global_load_dword v157, v[16:17], off offset:80 nt
	global_load_dword v158, v[16:17], off offset:88 nt
	global_load_dword v159, v[16:17], off offset:96 nt
	global_load_dword v160, v[16:17], off offset:104 nt
	global_load_dword v161, v[16:17], off offset:112 nt
	global_load_dword v162, v[16:17], off offset:120 nt
	global_load_dword v163, v[16:17], off offset:128 nt
	s_waitcnt vmcnt(0)
	v_mul_f32_e32 v100, v100, v132
	v_mul_f32_e32 v101, v101, v133
	v_mul_f32_e32 v102, v102, v134
	v_mul_f32_e32 v103, v103, v135
	v_mul_f32_e32 v104, v104, v136
	v_mul_f32_e32 v105, v105, v137
	v_mul_f32_e32 v106, v106, v138
	v_mul_f32_e32 v107, v107, v139
	v_mul_f32_e32 v108, v108, v140
	v_mul_f32_e32 v109, v109, v141
	v_mul_f32_e32 v110, v110, v142
	v_mul_f32_e32 v111, v111, v143
	v_mul_f32_e32 v112, v112, v144
	v_mul_f32_e32 v113, v113, v145
	v_mul_f32_e32 v114, v114, v146
	v_mul_f32_e32 v115, v115, v147
	v_mul_f32_e32 v116, v116, v148
	v_mul_f32_e32 v117, v117, v149
	v_mul_f32_e32 v118, v118, v150
	v_mul_f32_e32 v119, v119, v151
	v_mul_f32_e32 v120, v120, v152
	v_mul_f32_e32 v121, v121, v153
	v_mul_f32_e32 v122, v122, v154
	v_mul_f32_e32 v123, v123, v155
	v_mul_f32_e32 v124, v124, v156
	v_mul_f32_e32 v125, v125, v157
	v_mul_f32_e32 v126, v126, v158
	v_mul_f32_e32 v127, v127, v159
	v_mul_f32_e32 v128, v128, v160
	v_mul_f32_e32 v129, v129, v161
	v_mul_f32_e32 v130, v130, v162
	v_mul_f32_e32 v131, v131, v163
.Ltrm_nogain:
	s_waitcnt vmcnt(0)
	ds_write_b32 v4, v100
	ds_write_b32 v4, v101 offset:264
	ds_write_b32 v4, v102 offset:528
	ds_write_b32 v4, v103 offset:792
	ds_write_b32 v4, v104 offset:1056
	ds_write_b32 v4, v105 offset:1320
	ds_write_b32 v4, v106 offset:1584
	ds_write_b32 v4, v107 offset:1848
	ds_write_b32 v4, v108 offset:2112
	ds_write_b32 v4, v109 offset:2376
	ds_write_b32 v4, v110 offset:2640
	ds_write_b32 v4, v111 offset:2904
	ds_write_b32 v4, v112 offset:3168
	ds_write_b32 v4, v113 offset:3432
	ds_write_b32 v4, v114 offset:3696
	ds_write_b32 v4, v115 offset:3960
	ds_write_b32 v4, v116 offset:4224
	ds_write_b32 v4, v117 offset:4488
	ds_write_b32 v4, v118 offset:4752
	ds_write_b32 v4, v119 offset:5016
	ds_write_b32 v4, v120 offset:5280
	ds_write_b32 v4, v121 offset:5544
	ds_write_b32 v4, v122 offset:5808
	ds_write_b32 v4, v123 offset:6072
	ds_write_b32 v4, v124 offset:6336
	ds_write_b32 v4, v125 offset:6600
	ds_write_b32 v4, v126 offset:6864
	ds_write_b32 v4, v127 offset:7128
	ds_write_b32 v4, v128 offset:7392
	ds_write_b32 v4, v129 offset:7656
	ds_write_b32 v4, v130 offset:7920
	ds_write_b32 v4, v131 offset:8184
	s_branch .LBB0_117
